# hgrn pass2 output tiles software-pipelined: next tile LDS fragments in flight during MFMA chain, separate accumulators, delayed cvt+store
# baseline (speedup 1.0000x reference)
.LBB0_269:
	v_cvt_pk_bf16_f32 v48, v24, v25
	v_cvt_pk_bf16_f32 v49, v26, v27
	v_cvt_pk_bf16_f32 v50, v16, v17
	v_cvt_pk_bf16_f32 v51, v18, v19
	v_cvt_pk_bf16_f32 v52, v8, v9
	v_cvt_pk_bf16_f32 v53, v10, v11
	v_cvt_pk_bf16_f32 v54, v4, v5
	v_cvt_pk_bf16_f32 v55, v6, v7
	v_cvt_pk_bf16_f32 v56, v28, v29
	v_cvt_pk_bf16_f32 v57, v30, v31
	v_cvt_pk_bf16_f32 v58, v20, v21
	v_cvt_pk_bf16_f32 v59, v22, v23
	v_cndmask_b32_e64 v40, v40, 0, s[58:59]
	v_bfe_u32 v44, v40, 16, 1
	v_add3_u32 v40, v40, v44, s6
	v_cvt_pk_bf16_f32 v60, v12, v13
	ds_write_b16_d16_hi v126, v40
	v_cndmask_b32_e64 v40, v41, 0, s[60:61]
	v_bfe_u32 v41, v40, 16, 1
	v_add3_u32 v40, v40, v41, s6
	v_cvt_pk_bf16_f32 v61, v14, v15
	ds_write_b16_d16_hi v126, v40 offset:144
	v_cndmask_b32_e64 v40, v42, 0, s[62:63]
	v_bfe_u32 v41, v40, 16, 1
	v_add3_u32 v40, v40, v41, s6
	v_cvt_pk_bf16_f32 v62, v0, v1
	ds_write_b16_d16_hi v126, v40 offset:288
	v_cndmask_b32_e64 v40, v43, 0, s[64:65]
	v_bfe_u32 v41, v40, 16, 1
	v_add3_u32 v40, v40, v41, s6
	v_cvt_pk_bf16_f32 v63, v2, v3
	v_add_u32_e32 v138, 0x8800, v163
	ds_write_b16_d16_hi v126, v40 offset:432
	s_waitcnt lgkmcnt(0)
	s_barrier
	ds_read_b128 v[44:47], v127
	ds_read_b128 v[40:43], v127 offset:64
	ds_read_b128 v[172:175], v162
	ds_read_b128 v[184:187], v162 offset:64
	ds_read2_b64 v[188:191], v138 offset1:4
	ds_read2_b64 v[192:195], v138 offset0:8 offset1:12
	ds_read2_b64 v[196:199], v138 offset0:16 offset1:20
	ds_read2_b64 v[200:203], v138 offset0:24 offset1:28
	v_add_u32_e32 v182, 0x9800, v163
	ds_read_b128 v[204:207], v162 offset:2304
	ds_read_b128 v[208:211], v162 offset:2368
	ds_read2_b64 v[212:215], v182 offset0:32 offset1:36
	ds_read2_b64 v[216:219], v182 offset0:40 offset1:44
	ds_read2_b64 v[220:223], v182 offset0:48 offset1:52
	ds_read2_b64 v[224:227], v182 offset0:56 offset1:60
	s_waitcnt lgkmcnt(11)
	v_mfma_f32_16x16x32_bf16 v[142:145], v[44:47], v[172:175], 0
	s_waitcnt lgkmcnt(10)
	v_mfma_f32_16x16x32_bf16 v[142:145], v[40:43], v[184:187], v[142:145]
	s_waitcnt lgkmcnt(9)
	v_mfma_f32_16x16x32_bf16 v[142:145], v[48:51], v[188:191], v[142:145]
	s_waitcnt lgkmcnt(8)
	v_mfma_f32_16x16x32_bf16 v[142:145], v[52:55], v[192:195], v[142:145]
	s_waitcnt lgkmcnt(7)
	v_mfma_f32_16x16x32_bf16 v[142:145], v[56:59], v[196:199], v[142:145]
	s_waitcnt lgkmcnt(6)
	v_mfma_f32_16x16x32_bf16 v[142:145], v[60:63], v[200:203], v[142:145]
	v_add_u32_e32 v182, 0xa800, v163
	ds_read_b128 v[172:175], v162 offset:4608
	ds_read_b128 v[184:187], v162 offset:4672
	ds_read2_b64 v[188:191], v182 offset0:64 offset1:68
	ds_read2_b64 v[192:195], v182 offset0:72 offset1:76
	ds_read2_b64 v[196:199], v182 offset0:80 offset1:84
	ds_read2_b64 v[200:203], v182 offset0:88 offset1:92
	s_waitcnt lgkmcnt(11)
	v_mfma_f32_16x16x32_bf16 v[146:149], v[44:47], v[204:207], 0
	s_waitcnt lgkmcnt(10)
	v_mfma_f32_16x16x32_bf16 v[146:149], v[40:43], v[208:211], v[146:149]
	s_waitcnt lgkmcnt(9)
	v_mfma_f32_16x16x32_bf16 v[146:149], v[48:51], v[212:215], v[146:149]
	s_waitcnt lgkmcnt(8)
	v_mfma_f32_16x16x32_bf16 v[146:149], v[52:55], v[216:219], v[146:149]
	s_waitcnt lgkmcnt(7)
	v_mfma_f32_16x16x32_bf16 v[146:149], v[56:59], v[220:223], v[146:149]
	s_waitcnt lgkmcnt(6)
	v_mfma_f32_16x16x32_bf16 v[146:149], v[60:63], v[224:227], v[146:149]
	v_cvt_pk_bf16_f32 v240, v142, v143
	v_cvt_pk_bf16_f32 v241, v144, v145
	global_store_dwordx2 v[228:229], v[240:241], off
	v_add_u32_e32 v182, 0xb800, v163
	ds_read_b128 v[204:207], v162 offset:6912
	ds_read_b128 v[208:211], v162 offset:6976
	ds_read2_b64 v[212:215], v182 offset0:96 offset1:100
	ds_read2_b64 v[216:219], v182 offset0:104 offset1:108
	ds_read2_b64 v[220:223], v182 offset0:112 offset1:116
	ds_read2_b64 v[224:227], v182 offset0:120 offset1:124
	s_waitcnt lgkmcnt(11)
	v_mfma_f32_16x16x32_bf16 v[130:133], v[44:47], v[172:175], 0
	s_waitcnt lgkmcnt(10)
	v_mfma_f32_16x16x32_bf16 v[130:133], v[40:43], v[184:187], v[130:133]
	s_waitcnt lgkmcnt(9)
	v_mfma_f32_16x16x32_bf16 v[130:133], v[48:51], v[188:191], v[130:133]
	s_waitcnt lgkmcnt(8)
	v_mfma_f32_16x16x32_bf16 v[130:133], v[52:55], v[192:195], v[130:133]
	s_waitcnt lgkmcnt(7)
	v_mfma_f32_16x16x32_bf16 v[130:133], v[56:59], v[196:199], v[130:133]
	s_waitcnt lgkmcnt(6)
	v_mfma_f32_16x16x32_bf16 v[130:133], v[60:63], v[200:203], v[130:133]
	v_cvt_pk_bf16_f32 v242, v146, v147
	v_cvt_pk_bf16_f32 v243, v148, v149
	global_store_dwordx2 v[230:231], v[242:243], off
	v_add_u32_e32 v138, s16, v100
	v_add_u32_e32 v139, v156, v157
	ds_read_b128 v[172:175], v139 offset:63232
	ds_read_b128 v[184:187], v139 offset:63296
	ds_read_b128 v[188:191], v166
	ds_read_b128 v[192:195], v164 offset:60928
	ds_read_b128 v[196:199], v164 offset:60992
	ds_read_b128 v[200:203], v167
	s_waitcnt lgkmcnt(11)
	v_mfma_f32_16x16x32_bf16 v[134:137], v[44:47], v[204:207], 0
	s_waitcnt lgkmcnt(10)
	v_mfma_f32_16x16x32_bf16 v[134:137], v[40:43], v[208:211], v[134:137]
	s_waitcnt lgkmcnt(9)
	v_mfma_f32_16x16x32_bf16 v[134:137], v[48:51], v[212:215], v[134:137]
	s_waitcnt lgkmcnt(8)
	v_mfma_f32_16x16x32_bf16 v[134:137], v[52:55], v[216:219], v[134:137]
	s_waitcnt lgkmcnt(7)
	v_mfma_f32_16x16x32_bf16 v[134:137], v[56:59], v[220:223], v[134:137]
	s_waitcnt lgkmcnt(6)
	v_mfma_f32_16x16x32_bf16 v[134:137], v[60:63], v[224:227], v[134:137]
	v_cvt_pk_bf16_f32 v240, v130, v131
	v_cvt_pk_bf16_f32 v241, v132, v133
	global_store_dwordx2 v[232:233], v[240:241], off
	ds_read_b128 v[48:51], v138
	ds_read_b128 v[60:63], v165
	ds_read_b128 v[52:55], v139 offset:60928
	ds_read_b128 v[56:59], v139 offset:60992
	ds_read_b128 v[204:207], v164 offset:63232
	ds_read_b128 v[208:211], v164 offset:63296
	s_nop 3
	v_cvt_pk_bf16_f32 v242, v134, v135
	v_cvt_pk_bf16_f32 v243, v136, v137
	global_store_dwordx2 v[234:235], v[242:243], off
	s_waitcnt lgkmcnt(4)
	v_pk_mul_f32 v[24:25], v[24:25], v[48:49]
	v_pk_mul_f32 v[26:27], v[26:27], v[50:51]
	v_pk_mul_f32 v[16:17], v[16:17], v[60:61]
	v_pk_mul_f32 v[18:19], v[18:19], v[62:63]
	v_pk_mul_f32 v[8:9], v[8:9], v[188:189]
	v_pk_mul_f32 v[10:11], v[10:11], v[190:191]
	v_pk_mul_f32 v[4:5], v[4:5], v[200:201]
	v_pk_mul_f32 v[6:7], v[6:7], v[202:203]
	v_mfma_f32_16x16x32_bf16 v[16:19], v[172:175], v[44:47], v[16:19]
	v_mfma_f32_16x16x32_bf16 v[8:11], v[192:195], v[44:47], v[8:11]
	v_mfma_f32_16x16x32_bf16 v[16:19], v[184:187], v[40:43], v[16:19]
	v_mfma_f32_16x16x32_bf16 v[8:11], v[196:199], v[40:43], v[8:11]
	s_waitcnt lgkmcnt(2)
	v_mfma_f32_16x16x32_bf16 v[24:27], v[52:55], v[44:47], v[24:27]
	v_mfma_f32_16x16x32_bf16 v[24:27], v[56:59], v[40:43], v[24:27]
	s_waitcnt lgkmcnt(0)
	v_mfma_f32_16x16x32_bf16 v[4:7], v[204:207], v[44:47], v[4:7]
	v_mfma_f32_16x16x32_bf16 v[4:7], v[208:211], v[40:43], v[4:7]
	ds_read_b128 v[48:51], v158 offset:9216
	ds_read_b128 v[52:55], v158 offset:9280
	ds_read_b128 v[56:59], v138 offset:256
	ds_read_b128 v[60:63], v138 offset:320
	ds_read_b128 v[172:175], v158 offset:11520
	ds_read_b128 v[184:187], v158 offset:11584
	ds_read_b128 v[188:191], v158 offset:13824
	ds_read_b128 v[192:195], v158 offset:13888
	ds_read_b128 v[196:199], v138 offset:384
	ds_read_b128 v[200:203], v138 offset:448
	ds_read_b128 v[204:207], v158 offset:16128
	ds_read_b128 v[208:211], v158 offset:16192
	s_waitcnt lgkmcnt(9)
	v_pk_mul_f32 v[28:29], v[28:29], v[56:57]
	v_pk_mul_f32 v[30:31], v[30:31], v[58:59]
	s_waitcnt lgkmcnt(8)
	v_pk_mul_f32 v[20:21], v[20:21], v[60:61]
	v_pk_mul_f32 v[22:23], v[22:23], v[62:63]
	s_waitcnt lgkmcnt(3)
	v_pk_mul_f32 v[12:13], v[12:13], v[196:197]
	v_pk_mul_f32 v[14:15], v[14:15], v[198:199]
	s_waitcnt lgkmcnt(2)
	v_pk_mul_f32 v[0:1], v[0:1], v[200:201]
	v_pk_mul_f32 v[2:3], v[2:3], v[202:203]
	v_mfma_f32_16x16x32_bf16 v[28:31], v[48:51], v[44:47], v[28:31]
	v_mfma_f32_16x16x32_bf16 v[20:23], v[172:175], v[44:47], v[20:23]
	v_mfma_f32_16x16x32_bf16 v[12:15], v[188:191], v[44:47], v[12:15]
	s_waitcnt lgkmcnt(1)
	v_mfma_f32_16x16x32_bf16 v[0:3], v[204:207], v[44:47], v[0:3]
	v_mfma_f32_16x16x32_bf16 v[28:31], v[52:55], v[40:43], v[28:31]
	v_mfma_f32_16x16x32_bf16 v[20:23], v[184:187], v[40:43], v[20:23]
	v_mfma_f32_16x16x32_bf16 v[12:15], v[192:195], v[40:43], v[12:15]
	s_waitcnt lgkmcnt(0)
	v_mfma_f32_16x16x32_bf16 v[0:3], v[208:211], v[40:43], v[0:3]
	v_lshl_add_u64 v[228:229], v[228:229], 0, v[236:237]
	v_lshl_add_u64 v[230:231], v[230:231], 0, v[236:237]
	v_lshl_add_u64 v[232:233], v[232:233], 0, v[236:237]
	v_lshl_add_u64 v[234:235], v[234:235], 0, v[236:237]
	s_add_i32 s21, s21, 64
	s_sub_i32 s19, s19, 64
	s_cmpk_lg_i32 s21, 0x400
	s_barrier
	s_cbranch_scc0 .LBB0_260
